# scan: consumer waves s_sleep 2 right after barrier A so the producers' segment-prefix LDS reads (critical path) are served first
# speedup vs baseline: 1.0128x; 1.0128x over previous
.LBB0_392:
	s_waitcnt lgkmcnt(0)
	s_barrier
	s_sleep 2
	s_andn2_b64 vcc, exec, s[70:71]
	s_cbranch_vccnz .LBB0_386
	ds_read_b128 v[110:113], v89
	v_lshlrev_b32_e32 v114, 1, v85
	v_add3_u32 v118, s88, v105, v114
	ds_read_b128 v[114:117], v118 offset:36352
	s_movk_i32 s72, 0x2000
	s_waitcnt lgkmcnt(0)
	v_mfma_f32_32x32x16_bf16 v[50:65], v[110:113], v[114:117], v[50:65]
	ds_read_b128 v[110:113], v89 offset:32
	ds_read_b128 v[114:117], v118 offset:36384
	s_waitcnt lgkmcnt(0)
	v_mfma_f32_32x32x16_bf16 v[34:49], v[110:113], v[114:117], v[34:49]
	s_nop 11
	v_add_f32_e32 v34, v50, v34
	v_add_f32_e32 v35, v51, v35
	v_add_f32_e32 v36, v52, v36
	v_add_f32_e32 v37, v53, v37
	v_cvt_pk_bf16_f32 v34, v34, s0
	v_cvt_pk_bf16_f32 v35, v35, s0
	v_cvt_pk_bf16_f32 v36, v36, s0
	v_cvt_pk_bf16_f32 v37, v37, s0
	global_store_short v[80:81], v34, off
	global_store_short v[80:81], v35, off offset:1024
	global_store_short v[80:81], v36, off offset:2048
	global_store_short v[80:81], v37, off offset:3072
	v_add_f32_e32 v34, v54, v38
	v_cvt_pk_bf16_f32 v36, v34, s0
	v_add_co_u32_e32 v34, vcc, s72, v80
	s_movk_i32 s72, 0x4000
	s_nop 0
	v_addc_co_u32_e32 v35, vcc, 0, v81, vcc
	global_store_short v[34:35], v36, off
	v_add_f32_e32 v36, v55, v39
	v_cvt_pk_bf16_f32 v36, v36, s0
	global_store_short v[34:35], v36, off offset:1024
	v_add_f32_e32 v36, v56, v40
	v_cvt_pk_bf16_f32 v36, v36, s0
	global_store_short v[34:35], v36, off offset:2048
	v_add_f32_e32 v36, v57, v41
	v_cvt_pk_bf16_f32 v36, v36, s0
	global_store_short v[34:35], v36, off offset:3072
	v_add_f32_e32 v34, v58, v42
	v_cvt_pk_bf16_f32 v36, v34, s0
	v_add_co_u32_e32 v34, vcc, s72, v80
	s_movk_i32 s72, 0x6000
	s_nop 0
	v_addc_co_u32_e32 v35, vcc, 0, v81, vcc
	global_store_short v[34:35], v36, off
	v_add_f32_e32 v36, v59, v43
	v_cvt_pk_bf16_f32 v36, v36, s0
	global_store_short v[34:35], v36, off offset:1024
	v_add_f32_e32 v36, v60, v44
	v_cvt_pk_bf16_f32 v36, v36, s0
	global_store_short v[34:35], v36, off offset:2048
	v_add_f32_e32 v36, v61, v45
	v_cvt_pk_bf16_f32 v36, v36, s0
	global_store_short v[34:35], v36, off offset:3072
	v_add_f32_e32 v34, v62, v46
	v_cvt_pk_bf16_f32 v36, v34, s0
	v_add_co_u32_e32 v34, vcc, s72, v80
	s_nop 1
	v_addc_co_u32_e32 v35, vcc, 0, v81, vcc
	global_store_short v[34:35], v36, off
	v_add_f32_e32 v36, v63, v47
	v_cvt_pk_bf16_f32 v36, v36, s0
	global_store_short v[34:35], v36, off offset:1024
	v_add_f32_e32 v36, v64, v48
	v_cvt_pk_bf16_f32 v36, v36, s0
	global_store_short v[34:35], v36, off offset:2048
	v_add_f32_e32 v36, v65, v49
	v_cvt_pk_bf16_f32 v36, v36, s0
	global_store_short v[34:35], v36, off offset:3072
	s_branch .LBB0_386

.LBB0_423:
	s_waitcnt lgkmcnt(0)
	s_barrier
	s_sleep 2
	s_andn2_b64 vcc, exec, s[72:73]
	s_cbranch_vccnz .LBB0_417
	ds_read_b128 v[112:115], v89
	v_add3_u32 v111, s86, v105, v110
	ds_read_b128 v[116:119], v111 offset:36352
	ds_read_b128 v[120:123], v89 offset:32
	s_mov_b32 s92, 0x2c002000
	s_waitcnt lgkmcnt(1)
	v_mfma_f32_32x32x16_bf16 v[50:65], v[112:115], v[116:119], v[50:65]
	ds_read_b128 v[112:115], v111 offset:36384
	v_lshl_add_u64 v[116:117], v[80:81], 0, s[74:75]
	v_add_co_u32_e32 v118, vcc, 0x2c000000, v116
	s_nop 1
	v_addc_co_u32_e32 v119, vcc, 0, v117, vcc
	s_waitcnt lgkmcnt(0)
	v_mfma_f32_32x32x16_bf16 v[34:49], v[120:123], v[112:115], v[34:49]
	s_nop 11
	v_add_f32_e32 v34, v50, v34
	v_add_f32_e32 v35, v51, v35
	v_add_f32_e32 v36, v52, v36
	v_cvt_pk_bf16_f32 v34, v34, s0
	v_cvt_pk_bf16_f32 v35, v35, s0
	global_store_short v[118:119], v34, off
	global_store_short v[118:119], v35, off offset:1024
	v_cvt_pk_bf16_f32 v34, v36, s0
	global_store_short v[118:119], v34, off offset:2048
	v_add_f32_e32 v34, v53, v37
	v_cvt_pk_bf16_f32 v34, v34, s0
	global_store_short v[118:119], v34, off offset:3072
	v_add_f32_e32 v34, v54, v38
	v_cvt_pk_bf16_f32 v36, v34, s0
	v_add_co_u32_e32 v34, vcc, s92, v116
	s_mov_b32 s92, 0x2c004000
	s_nop 0
	v_addc_co_u32_e32 v35, vcc, 0, v117, vcc
	global_store_short v[34:35], v36, off
	v_add_f32_e32 v36, v55, v39
	v_cvt_pk_bf16_f32 v36, v36, s0
	global_store_short v[34:35], v36, off offset:1024
	v_add_f32_e32 v36, v56, v40
	v_cvt_pk_bf16_f32 v36, v36, s0
	global_store_short v[34:35], v36, off offset:2048
	v_add_f32_e32 v36, v57, v41
	v_cvt_pk_bf16_f32 v36, v36, s0
	global_store_short v[34:35], v36, off offset:3072
	v_add_f32_e32 v34, v58, v42
	v_cvt_pk_bf16_f32 v36, v34, s0
	v_add_co_u32_e32 v34, vcc, s92, v116
	s_mov_b32 s92, 0x2c006000
	s_nop 0
	v_addc_co_u32_e32 v35, vcc, 0, v117, vcc
	global_store_short v[34:35], v36, off
	v_add_f32_e32 v36, v59, v43
	v_cvt_pk_bf16_f32 v36, v36, s0
	global_store_short v[34:35], v36, off offset:1024
	v_add_f32_e32 v36, v60, v44
	v_cvt_pk_bf16_f32 v36, v36, s0
	global_store_short v[34:35], v36, off offset:2048
	v_add_f32_e32 v36, v61, v45
	v_cvt_pk_bf16_f32 v36, v36, s0
	global_store_short v[34:35], v36, off offset:3072
	v_add_f32_e32 v34, v62, v46
	v_cvt_pk_bf16_f32 v36, v34, s0
	v_add_co_u32_e32 v34, vcc, s92, v116
	s_nop 1
	v_addc_co_u32_e32 v35, vcc, 0, v117, vcc
	global_store_short v[34:35], v36, off
	v_add_f32_e32 v36, v63, v47
	v_cvt_pk_bf16_f32 v36, v36, s0
	global_store_short v[34:35], v36, off offset:1024
	v_add_f32_e32 v36, v64, v48
	v_cvt_pk_bf16_f32 v36, v36, s0
	global_store_short v[34:35], v36, off offset:2048
	v_add_f32_e32 v36, v65, v49
	v_cvt_pk_bf16_f32 v36, v36, s0
	global_store_short v[34:35], v36, off offset:3072
	s_branch .LBB0_417
